# in-proj: the workgroups with three units start about 8 us later than the 104 workgroups with four (two s_sleep 127), so the two classes' unit boundaries and start-up loads no longer coincide
# speedup vs baseline: 1.0182x; 1.0034x over previous
.LBB0_439:
	s_andn2_b64 vcc, exec, s[90:91]
	s_cbranch_vccnz .LBB0_590
	v_readlane_b32 s6, v236, 46
	s_mul_i32 s0, s6, 0x1b00000
	s_mul_hi_i32 s1, s6, 0x1b00000
	s_add_u32 s0, s10, s0
	s_addc_u32 s1, s11, s1
	v_readlane_b32 s7, v236, 47
	s_add_u32 s16, s10, 0xa000000
	s_addc_u32 s17, s11, 0
	s_lshl_b64 s[14:15], s[6:7], 21
	s_add_u32 s2, s10, s14
	s_addc_u32 s18, s11, s15
	s_add_u32 s40, s2, 0x9000000
	s_addc_u32 s41, s18, 0
	s_lshl_b32 s14, s6, 9
	s_ashr_i32 s15, s14, 31
	s_lshl_b64 s[14:15], s[14:15], 1
	s_add_u32 s14, s10, s14
	s_addc_u32 s15, s11, s15
	s_add_u32 s42, s14, 0xa100000
	s_addc_u32 s43, s15, 0
	s_add_u32 s44, s0, 0x1500000
	s_addc_u32 s45, s1, 0
	s_add_u32 s46, s2, 0x9800000
	s_addc_u32 s47, s18, 0
	s_lshl_b64 s[14:15], s[6:7], 18
	s_add_u32 s2, s10, s14
	s_addc_u32 s14, s11, s15
	s_add_u32 s48, s2, 0xa200000
	s_mov_b32 s35, s30
	s_mov_b32 s30, s63
	s_mov_b32 s58, s62
	s_mov_b32 s33, s29
	s_mov_b64 s[28:29], s[84:85]
	s_mov_b32 s31, s87
	s_addc_u32 s49, s14, 0
	v_readlane_b32 s86, v237, 57
	s_nop 0
	s_cmp_lt_u32 s86, 0x68
	s_cbranch_scc1 .Lk0_nosleep
	s_sleep 127
	s_sleep 127
.Lk0_nosleep:
	s_mov_b32 s86, 0
	s_branch .LBB0_443
